# attn QK: drop redundant vmcnt waits (Q loads retire at first barrier)
# speedup vs baseline: 1.0077x; 1.0077x over previous
.LBB0_513:
	s_lshl_b32 s4, s76, 14
	s_add_i32 s4, s4, 0
	v_add3_u32 v132, s4, v221, v220
	ds_read_b128 v[128:131], v132
	ds_read_b128 v[132:135], v132 offset:8192
	v_add3_u32 v196, s4, v222, v220
	ds_read_b128 v[192:195], v196
	ds_read_b128 v[196:199], v196 offset:8192
	s_waitcnt lgkmcnt(3)
	v_mfma_f32_32x32x16_bf16 v[144:159], v[128:131], v[160:163], 0
	s_waitcnt lgkmcnt(2)
	v_mfma_f32_32x32x16_bf16 v[128:143], v[132:135], v[160:163], 0
	s_waitcnt lgkmcnt(1)
	v_mfma_f32_32x32x16_bf16 v[144:159], v[192:195], v[164:167], v[144:159]
	s_waitcnt lgkmcnt(0)
	v_mfma_f32_32x32x16_bf16 v[128:143], v[196:199], v[164:167], v[128:143]
	v_add3_u32 v196, s4, v223, v220
	ds_read_b128 v[192:195], v196
	ds_read_b128 v[196:199], v196 offset:8192
	s_waitcnt lgkmcnt(1)
	v_mfma_f32_32x32x16_bf16 v[144:159], v[192:195], v[168:171], v[144:159]
	s_waitcnt lgkmcnt(0)
	v_mfma_f32_32x32x16_bf16 v[128:143], v[196:199], v[168:171], v[128:143]
	v_add3_u32 v196, s4, v224, v220
	ds_read_b128 v[192:195], v196
	ds_read_b128 v[196:199], v196 offset:8192
	s_waitcnt lgkmcnt(1)
	v_mfma_f32_32x32x16_bf16 v[144:159], v[192:195], v[172:175], v[144:159]
	s_waitcnt lgkmcnt(0)
	v_mfma_f32_32x32x16_bf16 v[128:143], v[196:199], v[172:175], v[128:143]
	v_add3_u32 v196, s4, v225, v220
	ds_read_b128 v[192:195], v196
	ds_read_b128 v[196:199], v196 offset:8192
	s_waitcnt lgkmcnt(1)
	v_mfma_f32_32x32x16_bf16 v[144:159], v[192:195], v[176:179], v[144:159]
	s_waitcnt lgkmcnt(0)
	v_mfma_f32_32x32x16_bf16 v[128:143], v[196:199], v[176:179], v[128:143]
	v_add3_u32 v196, s4, v227, v220
	ds_read_b128 v[192:195], v196
	ds_read_b128 v[196:199], v196 offset:8192
	s_waitcnt lgkmcnt(1)
	v_mfma_f32_32x32x16_bf16 v[144:159], v[192:195], v[180:183], v[144:159]
	s_waitcnt lgkmcnt(0)
	v_mfma_f32_32x32x16_bf16 v[128:143], v[196:199], v[180:183], v[128:143]
	v_add3_u32 v196, s4, v228, v220
	ds_read_b128 v[192:195], v196
	ds_read_b128 v[196:199], v196 offset:8192
	s_waitcnt lgkmcnt(1)
	v_mfma_f32_32x32x16_bf16 v[144:159], v[192:195], v[184:187], v[144:159]
	s_waitcnt lgkmcnt(0)
	v_mfma_f32_32x32x16_bf16 v[128:143], v[196:199], v[184:187], v[128:143]
	v_add3_u32 v196, s4, v229, v220
	ds_read_b128 v[192:195], v196
	ds_read_b128 v[196:199], v196 offset:8192
	s_waitcnt lgkmcnt(1)
	v_mfma_f32_32x32x16_bf16 v[144:159], v[192:195], v[188:191], v[144:159]
	s_waitcnt lgkmcnt(0)
	v_mfma_f32_32x32x16_bf16 v[128:143], v[196:199], v[188:191], v[128:143]
	s_nop 9
	v_max_f32_e32 v192, v145, v145
	v_max_f32_e32 v193, v144, v144
	v_max_f32_e32 v192, v193, v192
	v_max3_f32 v192, v192, v146, v147
	v_max3_f32 v192, v192, v148, v149
	v_max3_f32 v192, v192, v150, v151
	v_max3_f32 v192, v192, v152, v153
	v_max3_f32 v192, v192, v154, v155
	v_max3_f32 v192, v192, v156, v157
	v_max3_f32 v192, v192, v158, v159
	v_max3_f32 v192, v192, v128, v129
	v_max3_f32 v192, v192, v130, v131
	v_max3_f32 v192, v192, v132, v133
	v_max3_f32 v192, v192, v134, v135
	v_max3_f32 v192, v192, v136, v137
	v_max3_f32 v192, v192, v138, v139
	v_max3_f32 v192, v192, v140, v141
	v_max3_f32 v192, v192, v142, v143
	v_mov_b32_e32 v193, v192
	s_nop 1
	v_permlane32_swap_b32_e32 v192, v193
	v_max_f32_e32 v193, v193, v193
	v_max_f32_e32 v192, v192, v192
	v_max_f32_e32 v192, v192, v193
	v_sub_f32_e32 v193, v192, v231
	v_cmp_ge_f32_e32 vcc, s38, v193
	v_max_f32_e32 v193, v231, v231
	v_max_f32_e32 v234, v193, v192
	v_sub_f32_e32 v192, v231, v234
	v_mul_f32_e32 v192, 0x3e0293ee, v192
	v_exp_f32_e32 v192, v192
	s_cmp_eq_u64 vcc, exec
	s_cselect_b64 s[4:5], -1, 0
	v_cndmask_b32_e64 v233, v192, 1.0, s[4:5]
	v_cmp_gt_f32_e32 vcc, 1.0, v233
	s_cbranch_vccz .LBB0_517
	s_and_saveexec_b64 s[24:25], s[0:1]
	ds_write_b32 v226, v233 offset:128
	s_or_b64 exec, exec, s[24:25]
	s_waitcnt lgkmcnt(0)
	v_add_u32_e32 v192, s21, v210
	ds_read_b128 v[204:207], v192 offset:224
	ds_read_b128 v[200:203], v192 offset:192
	ds_read_b128 v[196:199], v192 offset:160
	ds_read_b128 v[192:195], v192 offset:128
	s_waitcnt lgkmcnt(3)
	v_pk_mul_f32 v[12:13], v[12:13], v[204:205]
	s_waitcnt lgkmcnt(2)
	v_pk_mul_f32 v[8:9], v[8:9], v[200:201]
	s_waitcnt lgkmcnt(1)
	v_pk_mul_f32 v[4:5], v[4:5], v[196:197]
	v_pk_mul_f32 v[14:15], v[14:15], v[206:207]
	v_pk_mul_f32 v[10:11], v[10:11], v[202:203]
	v_pk_mul_f32 v[6:7], v[6:7], v[198:199]
	s_waitcnt lgkmcnt(0)
	v_pk_mul_f32 v[2:3], v[2:3], v[194:195]
	v_pk_mul_f32 v[0:1], v[0:1], v[192:193]
	v_pk_mul_f32 v[124:125], v[124:125], v[204:205]
	v_pk_mul_f32 v[120:121], v[120:121], v[200:201]
	v_pk_mul_f32 v[116:117], v[116:117], v[196:197]
	v_pk_mul_f32 v[126:127], v[126:127], v[206:207]
	v_pk_mul_f32 v[122:123], v[122:123], v[202:203]
	v_pk_mul_f32 v[118:119], v[118:119], v[198:199]
	v_pk_mul_f32 v[114:115], v[114:115], v[194:195]
	v_pk_mul_f32 v[112:113], v[112:113], v[192:193]
	v_pk_mul_f32 v[108:109], v[108:109], v[204:205]
	v_pk_mul_f32 v[104:105], v[104:105], v[200:201]
	v_pk_mul_f32 v[100:101], v[100:101], v[196:197]
	v_pk_mul_f32 v[110:111], v[110:111], v[206:207]
	v_pk_mul_f32 v[106:107], v[106:107], v[202:203]
	v_pk_mul_f32 v[102:103], v[102:103], v[198:199]
	v_pk_mul_f32 v[98:99], v[98:99], v[194:195]
	v_pk_mul_f32 v[96:97], v[96:97], v[192:193]
	v_pk_mul_f32 v[92:93], v[92:93], v[204:205]
	v_pk_mul_f32 v[88:89], v[88:89], v[200:201]
	v_pk_mul_f32 v[84:85], v[84:85], v[196:197]
	v_pk_mul_f32 v[94:95], v[94:95], v[206:207]
	v_pk_mul_f32 v[90:91], v[90:91], v[202:203]
	v_pk_mul_f32 v[86:87], v[86:87], v[198:199]
	v_pk_mul_f32 v[82:83], v[82:83], v[194:195]
	v_pk_mul_f32 v[80:81], v[80:81], v[192:193]
	v_pk_mul_f32 v[76:77], v[76:77], v[204:205]
	v_pk_mul_f32 v[72:73], v[72:73], v[200:201]
	v_pk_mul_f32 v[68:69], v[68:69], v[196:197]
	v_pk_mul_f32 v[78:79], v[78:79], v[206:207]
	v_pk_mul_f32 v[74:75], v[74:75], v[202:203]
	v_pk_mul_f32 v[70:71], v[70:71], v[198:199]
	v_pk_mul_f32 v[66:67], v[66:67], v[194:195]
	v_pk_mul_f32 v[64:65], v[64:65], v[192:193]
	v_pk_mul_f32 v[60:61], v[60:61], v[204:205]
	v_pk_mul_f32 v[56:57], v[56:57], v[200:201]
	v_pk_mul_f32 v[52:53], v[52:53], v[196:197]
	v_pk_mul_f32 v[62:63], v[62:63], v[206:207]
	v_pk_mul_f32 v[58:59], v[58:59], v[202:203]
	v_pk_mul_f32 v[54:55], v[54:55], v[198:199]
	v_pk_mul_f32 v[50:51], v[50:51], v[194:195]
	v_pk_mul_f32 v[48:49], v[48:49], v[192:193]
	v_pk_mul_f32 v[44:45], v[44:45], v[204:205]
	v_pk_mul_f32 v[40:41], v[40:41], v[200:201]
	v_pk_mul_f32 v[36:37], v[36:37], v[196:197]
	v_pk_mul_f32 v[46:47], v[46:47], v[206:207]
	v_pk_mul_f32 v[42:43], v[42:43], v[202:203]
	v_pk_mul_f32 v[38:39], v[38:39], v[198:199]
	v_pk_mul_f32 v[34:35], v[34:35], v[194:195]
	v_pk_mul_f32 v[32:33], v[32:33], v[192:193]
	v_pk_mul_f32 v[28:29], v[28:29], v[204:205]
	v_pk_mul_f32 v[24:25], v[24:25], v[200:201]
	v_pk_mul_f32 v[20:21], v[20:21], v[196:197]
	v_pk_mul_f32 v[30:31], v[30:31], v[206:207]
	v_pk_mul_f32 v[26:27], v[26:27], v[202:203]
	v_pk_mul_f32 v[22:23], v[22:23], v[198:199]
	v_pk_mul_f32 v[18:19], v[18:19], v[194:195]
	v_pk_mul_f32 v[16:17], v[16:17], v[192:193]

.LBB0_906:
	s_lshl_b32 s4, s80, 14
	s_add_i32 s4, s4, 0
	v_add3_u32 v132, s4, v221, v220
	ds_read_b128 v[128:131], v132
	ds_read_b128 v[132:135], v132 offset:8192
	v_add3_u32 v196, s4, v222, v220
	ds_read_b128 v[192:195], v196
	ds_read_b128 v[196:199], v196 offset:8192
	v_add3_u32 v200, s4, v227, v220
	s_waitcnt lgkmcnt(3)
	v_mfma_f32_32x32x16_bf16 v[144:159], v[128:131], v[160:163], 0
	s_waitcnt lgkmcnt(2)
	v_mfma_f32_32x32x16_bf16 v[128:143], v[132:135], v[160:163], 0
	s_waitcnt lgkmcnt(1)
	v_mfma_f32_32x32x16_bf16 v[144:159], v[192:195], v[164:167], v[144:159]
	s_waitcnt lgkmcnt(0)
	v_mfma_f32_32x32x16_bf16 v[128:143], v[196:199], v[164:167], v[128:143]
	v_add3_u32 v196, s4, v223, v220
	ds_read_b128 v[192:195], v196
	ds_read_b128 v[196:199], v196 offset:8192
	s_waitcnt lgkmcnt(1)
	v_mfma_f32_32x32x16_bf16 v[144:159], v[192:195], v[168:171], v[144:159]
	s_waitcnt lgkmcnt(0)
	v_mfma_f32_32x32x16_bf16 v[128:143], v[196:199], v[168:171], v[128:143]
	v_add3_u32 v196, s4, v225, v220
	ds_read_b128 v[192:195], v196
	ds_read_b128 v[196:199], v196 offset:8192
	s_waitcnt lgkmcnt(1)
	v_mfma_f32_32x32x16_bf16 v[144:159], v[192:195], v[172:175], v[144:159]
	s_waitcnt lgkmcnt(0)
	v_mfma_f32_32x32x16_bf16 v[128:143], v[196:199], v[172:175], v[128:143]
	v_add3_u32 v196, s4, v226, v220
	ds_read_b128 v[192:195], v196
	ds_read_b128 v[196:199], v196 offset:8192
	s_waitcnt lgkmcnt(1)
	v_mfma_f32_32x32x16_bf16 v[144:159], v[192:195], v[176:179], v[144:159]
	s_waitcnt lgkmcnt(0)
	v_mfma_f32_32x32x16_bf16 v[128:143], v[196:199], v[176:179], v[128:143]
	ds_read_b128 v[192:195], v200
	ds_read_b128 v[196:199], v200 offset:8192
	v_add3_u32 v200, s4, v228, v220
	s_waitcnt lgkmcnt(1)
	v_mfma_f32_32x32x16_bf16 v[144:159], v[192:195], v[180:183], v[144:159]
	s_waitcnt lgkmcnt(0)
	v_mfma_f32_32x32x16_bf16 v[128:143], v[196:199], v[180:183], v[128:143]
	ds_read_b128 v[192:195], v200
	ds_read_b128 v[196:199], v200 offset:8192
	v_add3_u32 v200, s4, v229, v220
	s_waitcnt lgkmcnt(1)
	v_mfma_f32_32x32x16_bf16 v[144:159], v[192:195], v[184:187], v[144:159]
	ds_read_b128 v[192:195], v200
	ds_read_b128 v[200:203], v200 offset:8192
	s_waitcnt lgkmcnt(1)
	v_mfma_f32_32x32x16_bf16 v[144:159], v[192:195], v[188:191], v[144:159]
	v_max_f32_e32 v194, v231, v231
	v_mfma_f32_32x32x16_bf16 v[128:143], v[196:199], v[184:187], v[128:143]
	s_nop 9
	v_max_f32_e32 v192, v145, v145
	v_max_f32_e32 v193, v144, v144
	v_max_f32_e32 v192, v193, v192
	v_max3_f32 v192, v192, v146, v147
	v_max3_f32 v192, v192, v148, v149
	v_max3_f32 v192, v192, v150, v151
	v_max3_f32 v192, v192, v152, v153
	s_waitcnt lgkmcnt(0)
	v_mfma_f32_32x32x16_bf16 v[128:143], v[200:203], v[188:191], v[128:143]
	v_max3_f32 v192, v192, v154, v155
	v_max3_f32 v192, v192, v156, v157
	v_max3_f32 v192, v192, v158, v159
	s_nop 8
	v_max3_f32 v192, v192, v128, v129
	v_max3_f32 v192, v192, v130, v131
	v_max3_f32 v192, v192, v132, v133
	v_max3_f32 v192, v192, v134, v135
	v_max3_f32 v192, v192, v136, v137
	v_max3_f32 v192, v192, v138, v139
	v_max3_f32 v192, v192, v140, v141
	v_max3_f32 v192, v192, v142, v143
	v_mov_b32_e32 v193, v192
	s_nop 1
	v_permlane32_swap_b32_e32 v192, v193
	v_max_f32_e32 v193, v193, v193
	v_max_f32_e32 v192, v192, v192
	v_max_f32_e32 v192, v192, v193
	v_max_f32_e32 v234, v194, v192
	v_sub_f32_e32 v193, v192, v231
	v_sub_f32_e32 v192, v231, v234
	v_mul_f32_e32 v192, 0x3e0293ee, v192
	v_exp_f32_e32 v192, v192
	v_cmp_ge_f32_e32 vcc, s42, v193
	s_cmp_eq_u64 vcc, exec
	s_cselect_b64 s[4:5], -1, 0
	v_cndmask_b32_e64 v233, v192, 1.0, s[4:5]
	v_cmp_gt_f32_e32 vcc, 1.0, v233
	s_cbranch_vccz .LBB0_910
	s_and_saveexec_b64 s[24:25], s[0:1]
	ds_write_b32 v224, v233 offset:128
	s_or_b64 exec, exec, s[24:25]
	s_waitcnt lgkmcnt(0)
	v_add_u32_e32 v192, s21, v210
	ds_read_b128 v[204:207], v192 offset:224
	ds_read_b128 v[200:203], v192 offset:192
	ds_read_b128 v[196:199], v192 offset:160
	ds_read_b128 v[192:195], v192 offset:128
	s_waitcnt lgkmcnt(3)
	v_pk_mul_f32 v[12:13], v[12:13], v[204:205]
	s_waitcnt lgkmcnt(2)
	v_pk_mul_f32 v[8:9], v[8:9], v[200:201]
	s_waitcnt lgkmcnt(1)
	v_pk_mul_f32 v[4:5], v[4:5], v[196:197]
	v_pk_mul_f32 v[14:15], v[14:15], v[206:207]
	v_pk_mul_f32 v[10:11], v[10:11], v[202:203]
	v_pk_mul_f32 v[6:7], v[6:7], v[198:199]
	s_waitcnt lgkmcnt(0)
	v_pk_mul_f32 v[2:3], v[2:3], v[194:195]
	v_pk_mul_f32 v[0:1], v[0:1], v[192:193]
	v_pk_mul_f32 v[124:125], v[124:125], v[204:205]
	v_pk_mul_f32 v[120:121], v[120:121], v[200:201]
	v_pk_mul_f32 v[116:117], v[116:117], v[196:197]
	v_pk_mul_f32 v[126:127], v[126:127], v[206:207]
	v_pk_mul_f32 v[122:123], v[122:123], v[202:203]
	v_pk_mul_f32 v[118:119], v[118:119], v[198:199]
	v_pk_mul_f32 v[114:115], v[114:115], v[194:195]
	v_pk_mul_f32 v[112:113], v[112:113], v[192:193]
	v_pk_mul_f32 v[108:109], v[108:109], v[204:205]
	v_pk_mul_f32 v[104:105], v[104:105], v[200:201]
	v_pk_mul_f32 v[100:101], v[100:101], v[196:197]
	v_pk_mul_f32 v[110:111], v[110:111], v[206:207]
	v_pk_mul_f32 v[106:107], v[106:107], v[202:203]
	v_pk_mul_f32 v[102:103], v[102:103], v[198:199]
	v_pk_mul_f32 v[98:99], v[98:99], v[194:195]
	v_pk_mul_f32 v[96:97], v[96:97], v[192:193]
	v_pk_mul_f32 v[92:93], v[92:93], v[204:205]
	v_pk_mul_f32 v[88:89], v[88:89], v[200:201]
	v_pk_mul_f32 v[84:85], v[84:85], v[196:197]
	v_pk_mul_f32 v[94:95], v[94:95], v[206:207]
	v_pk_mul_f32 v[90:91], v[90:91], v[202:203]
	v_pk_mul_f32 v[86:87], v[86:87], v[198:199]
	v_pk_mul_f32 v[82:83], v[82:83], v[194:195]
	v_pk_mul_f32 v[80:81], v[80:81], v[192:193]
	v_pk_mul_f32 v[76:77], v[76:77], v[204:205]
	v_pk_mul_f32 v[72:73], v[72:73], v[200:201]
	v_pk_mul_f32 v[68:69], v[68:69], v[196:197]
	v_pk_mul_f32 v[78:79], v[78:79], v[206:207]
	v_pk_mul_f32 v[74:75], v[74:75], v[202:203]
	v_pk_mul_f32 v[70:71], v[70:71], v[198:199]
	v_pk_mul_f32 v[66:67], v[66:67], v[194:195]
	v_pk_mul_f32 v[64:65], v[64:65], v[192:193]
	v_pk_mul_f32 v[60:61], v[60:61], v[204:205]
	v_pk_mul_f32 v[56:57], v[56:57], v[200:201]
	v_pk_mul_f32 v[52:53], v[52:53], v[196:197]
	v_pk_mul_f32 v[62:63], v[62:63], v[206:207]
	v_pk_mul_f32 v[58:59], v[58:59], v[202:203]
	v_pk_mul_f32 v[54:55], v[54:55], v[198:199]
	v_pk_mul_f32 v[50:51], v[50:51], v[194:195]
	v_pk_mul_f32 v[48:49], v[48:49], v[192:193]
	v_pk_mul_f32 v[44:45], v[44:45], v[204:205]
	v_pk_mul_f32 v[40:41], v[40:41], v[200:201]
	v_pk_mul_f32 v[36:37], v[36:37], v[196:197]
	v_pk_mul_f32 v[46:47], v[46:47], v[206:207]
	v_pk_mul_f32 v[42:43], v[42:43], v[202:203]
	v_pk_mul_f32 v[38:39], v[38:39], v[198:199]
	v_pk_mul_f32 v[34:35], v[34:35], v[194:195]
	v_pk_mul_f32 v[32:33], v[32:33], v[192:193]
	v_pk_mul_f32 v[28:29], v[28:29], v[204:205]
	v_pk_mul_f32 v[24:25], v[24:25], v[200:201]
	v_pk_mul_f32 v[20:21], v[20:21], v[196:197]
	v_pk_mul_f32 v[30:31], v[30:31], v[206:207]
	v_pk_mul_f32 v[26:27], v[26:27], v[202:203]
	v_pk_mul_f32 v[22:23], v[22:23], v[198:199]
	v_pk_mul_f32 v[18:19], v[18:19], v[194:195]
	v_pk_mul_f32 v[16:17], v[16:17], v[192:193]
